# GDN chunk prep: interior chunks use a software-pipelined causal-conv path (row loads two taps ahead, weights three steps ahead)
# speedup vs baseline: 1.0645x; 1.0027x over previous
; DI void gdn_chain(const P& p, int cid, char* smem) {
;     ...
;       {
;         const int pos = c * 64 + pp;
;         const int tau = dir ? len - 1 - pos : pos;
;         float aq[16], ak[16], av[8];
; #pragma unroll
;         for (int i = 0; i < 16; ++i) { aq[i] = 0.f; ak[i] = 0.f; }
; #pragma unroll
;         for (int i = 0; i < 8; ++i) av[i] = 0.f;
; #pragma unroll
;         for (int j = 0; j < 5; ++j) {
;           const int tt = tau + j - 2;
;           if (tt >= 0 && tt < len) {
;             const u16* zr = z + (size_t)(base + tt) * EVEN_IN + h * 64;
;             float f[16];
;             unpack8(*(const uint4*)(zr + 672 + qd * 16), f); unpack8(*(const uint4*)(zr + 672 + qd * 16 + 8), f + 8);
; #pragma unroll
;             for (int i = 0; i < 16; ++i) aq[i] += cw[j * 160 + qd * 16 + i] * f[i];
;             unpack8(*(const uint4*)(zr + 1184 + qd * 16), f); unpack8(*(const uint4*)(zr + 1184 + qd * 16 + 8), f + 8);
; #pragma unroll
;             for (int i = 0; i < 16; ++i) ak[i] += cw[j * 160 + 64 + qd * 16 + i] * f[i];
;             unpack8(*(const uint4*)(zr + 1696 + eb * 32 + qd * 8), f);
; #pragma unroll
;             for (int i = 0; i < 8; ++i) av[i] += cw[j * 160 + 128 + qd * 8 + i] * f[i];
;           }
;         }
.LBB0_948:
	s_cmp_eq_u32 s54, 0
	s_cbranch_scc1 .Lgdn_slow
	s_add_u32 s0, s54, 1
	s_cmp_eq_u32 s0, s52
	s_cbranch_scc1 .Lgdn_slow
	v_lshl_add_u32 v8, s54, 6, v69
	v_xad_u32 v9, v8, -1, s48
	s_lshl_b32 s20, s45, 1
	v_cndmask_b32_e64 v83, v9, v8, s[74:75]
	v_lshlrev_b32_e32 v154, 1, v48
	v_lshl_add_u32 v155, v50, 1, s20
	v_add_u32_e32 v58, s49, v83
	v_add_u32_e32 v54, -2, v58
	v_mad_u32_u24 v57, v54, s7, v155
	v_mad_u32_u24 v56, v54, s7, v154
	global_load_dwordx4 v[224:227], v56, s[38:39] offset:1344
	global_load_dwordx4 v[228:231], v56, s[38:39] offset:1360
	global_load_dwordx4 v[232:235], v56, s[38:39] offset:2368
	global_load_dwordx4 v[236:239], v56, s[38:39] offset:2384
	global_load_dwordx4 v[240:243], v57, s[38:39] offset:3392
	v_add_u32_e32 v54, -1, v58
	v_mad_u32_u24 v65, v54, s7, v155
	v_mad_u32_u24 v64, v54, s7, v154
	global_load_dwordx4 v[244:247], v64, s[38:39] offset:1344
	global_load_dwordx4 v[248:251], v64, s[38:39] offset:1360
	global_load_dwordx4 v[252:255], v64, s[38:39] offset:2368
	global_load_dwordx4 v[124:127], v64, s[38:39] offset:2384
	global_load_dwordx4 v[128:131], v65, s[38:39] offset:3392
	ds_read_b128 v[84:87], v70 offset:50176
	ds_read_b128 v[88:91], v70 offset:50192
	ds_read_b128 v[92:95], v70 offset:50208
	ds_read_b128 v[98:101], v70 offset:50224
	ds_read_b128 v[102:105], v70 offset:50432
	ds_read_b128 v[106:109], v70 offset:50448
	v_mad_u32_u24 v97, v58, s7, v155
	v_mad_u32_u24 v59, v58, s7, v154
	ds_read_b128 v[120:123], v70 offset:50464
	ds_read_b128 v[60:63], v70 offset:50480
	s_waitcnt vmcnt(9)
	v_lshlrev_b32_e32 v54, 16, v224
	v_and_b32_e32 v55, 0xffff0000, v224
	v_lshlrev_b32_e32 v56, 16, v225
	v_and_b32_e32 v57, 0xffff0000, v225
	v_lshlrev_b32_e32 v64, 16, v226
	v_and_b32_e32 v65, 0xffff0000, v226
	v_lshlrev_b32_e32 v66, 16, v227
	v_and_b32_e32 v67, 0xffff0000, v227
	global_load_dwordx4 v[224:227], v59, s[38:39] offset:1344
	s_waitcnt lgkmcnt(7)
	v_pk_fma_f32 v[22:23], v[84:85], v[54:55], 0 op_sel_hi:[1,1,0]
	v_pk_fma_f32 v[20:21], v[86:87], v[56:57], 0 op_sel_hi:[1,1,0]
	s_waitcnt lgkmcnt(6)
	v_pk_fma_f32 v[18:19], v[88:89], v[64:65], 0 op_sel_hi:[1,1,0]
	v_pk_fma_f32 v[16:17], v[90:91], v[66:67], 0 op_sel_hi:[1,1,0]
	ds_read_b128 v[84:87], v74 offset:50688
	ds_read_b128 v[88:91], v74 offset:50704
	s_waitcnt vmcnt(9)
	v_lshlrev_b32_e32 v54, 16, v228
	v_and_b32_e32 v55, 0xffff0000, v228
	v_lshlrev_b32_e32 v56, 16, v229
	v_and_b32_e32 v57, 0xffff0000, v229
	v_lshlrev_b32_e32 v64, 16, v230
	v_and_b32_e32 v65, 0xffff0000, v230
	v_lshlrev_b32_e32 v66, 16, v231
	v_and_b32_e32 v67, 0xffff0000, v231
	global_load_dwordx4 v[228:231], v59, s[38:39] offset:1360
	s_waitcnt lgkmcnt(7)
	v_pk_fma_f32 v[14:15], v[92:93], v[54:55], 0 op_sel_hi:[1,1,0]
	v_pk_fma_f32 v[12:13], v[94:95], v[56:57], 0 op_sel_hi:[1,1,0]
	s_waitcnt lgkmcnt(6)
	v_pk_fma_f32 v[10:11], v[98:99], v[64:65], 0 op_sel_hi:[1,1,0]
	v_pk_fma_f32 v[8:9], v[100:101], v[66:67], 0 op_sel_hi:[1,1,0]
	ds_read_b128 v[92:95], v70 offset:50816
	ds_read_b128 v[98:101], v70 offset:50832
	s_waitcnt vmcnt(9)
	v_lshlrev_b32_e32 v54, 16, v232
	v_and_b32_e32 v55, 0xffff0000, v232
	v_lshlrev_b32_e32 v56, 16, v233
	v_and_b32_e32 v57, 0xffff0000, v233
	v_lshlrev_b32_e32 v64, 16, v234
	v_and_b32_e32 v65, 0xffff0000, v234
	v_lshlrev_b32_e32 v66, 16, v235
	v_and_b32_e32 v67, 0xffff0000, v235
	global_load_dwordx4 v[232:235], v59, s[38:39] offset:2368
	s_waitcnt lgkmcnt(7)
	v_pk_fma_f32 v[38:39], v[102:103], v[54:55], 0 op_sel_hi:[1,1,0]
	v_pk_fma_f32 v[36:37], v[104:105], v[56:57], 0 op_sel_hi:[1,1,0]
	s_waitcnt lgkmcnt(6)
	v_pk_fma_f32 v[34:35], v[106:107], v[64:65], 0 op_sel_hi:[1,1,0]
	v_pk_fma_f32 v[32:33], v[108:109], v[66:67], 0 op_sel_hi:[1,1,0]
	ds_read_b128 v[102:105], v70 offset:50848
	ds_read_b128 v[106:109], v70 offset:50864
	s_waitcnt vmcnt(9)
	v_lshlrev_b32_e32 v54, 16, v236
	v_and_b32_e32 v55, 0xffff0000, v236
	v_lshlrev_b32_e32 v56, 16, v237
	v_and_b32_e32 v57, 0xffff0000, v237
	v_lshlrev_b32_e32 v64, 16, v238
	v_and_b32_e32 v65, 0xffff0000, v238
	v_lshlrev_b32_e32 v66, 16, v239
	v_and_b32_e32 v67, 0xffff0000, v239
	global_load_dwordx4 v[236:239], v59, s[38:39] offset:2384
	s_waitcnt lgkmcnt(7)
	v_pk_fma_f32 v[30:31], v[120:121], v[54:55], 0 op_sel_hi:[1,1,0]
	v_pk_fma_f32 v[28:29], v[122:123], v[56:57], 0 op_sel_hi:[1,1,0]
	s_waitcnt lgkmcnt(6)
	v_pk_fma_f32 v[26:27], v[60:61], v[64:65], 0 op_sel_hi:[1,1,0]
	v_pk_fma_f32 v[24:25], v[62:63], v[66:67], 0 op_sel_hi:[1,1,0]
	ds_read_b128 v[120:123], v70 offset:51072
	ds_read_b128 v[60:63], v70 offset:51088
	s_waitcnt vmcnt(9)
	v_lshlrev_b32_e32 v54, 16, v240
	v_and_b32_e32 v55, 0xffff0000, v240
	v_lshlrev_b32_e32 v56, 16, v241
	v_and_b32_e32 v57, 0xffff0000, v241
	v_lshlrev_b32_e32 v64, 16, v242
	v_and_b32_e32 v65, 0xffff0000, v242
	v_lshlrev_b32_e32 v66, 16, v243
	v_and_b32_e32 v67, 0xffff0000, v243
	global_load_dwordx4 v[240:243], v97, s[38:39] offset:3392
	s_waitcnt lgkmcnt(7)
	v_pk_fma_f32 v[46:47], v[84:85], v[54:55], 0 op_sel_hi:[1,1,0]
	v_pk_fma_f32 v[40:41], v[86:87], v[56:57], 0 op_sel_hi:[1,1,0]
	s_waitcnt lgkmcnt(6)
	v_pk_fma_f32 v[42:43], v[88:89], v[64:65], 0 op_sel_hi:[1,1,0]
	v_pk_fma_f32 v[44:45], v[90:91], v[66:67], 0 op_sel_hi:[1,1,0]
	v_add_u32_e32 v59, 1, v58
	v_mad_u32_u24 v97, v59, s7, v155
	v_mad_u32_u24 v59, v59, s7, v154
	ds_read_b128 v[84:87], v70 offset:51104
	ds_read_b128 v[88:91], v70 offset:51120
	s_waitcnt vmcnt(9)
	v_lshlrev_b32_e32 v54, 16, v244
	v_and_b32_e32 v55, 0xffff0000, v244
	v_lshlrev_b32_e32 v56, 16, v245
	v_and_b32_e32 v57, 0xffff0000, v245
	v_lshlrev_b32_e32 v64, 16, v246
	v_and_b32_e32 v65, 0xffff0000, v246
	v_lshlrev_b32_e32 v66, 16, v247
	v_and_b32_e32 v67, 0xffff0000, v247
	global_load_dwordx4 v[244:247], v59, s[38:39] offset:1344
	s_waitcnt lgkmcnt(7)
; DI void gdn_chain(const P& p, int cid, char* smem) {
;     ...
;         for (int j = 0; j < 5; ++j) {
;           const int tt = tau + j - 2;
;           if (tt >= 0 && tt < len) {
;             const u16* zr = z + (size_t)(base + tt) * EVEN_IN + h * 64;
;             float f[16];
;             unpack8(*(const uint4*)(zr + 672 + qd * 16), f); unpack8(*(const uint4*)(zr + 672 + qd * 16 + 8), f + 8);
; #pragma unroll
;             for (int i = 0; i < 16; ++i) aq[i] += cw[j * 160 + qd * 16 + i] * f[i];
;             unpack8(*(const uint4*)(zr + 1184 + qd * 16), f); unpack8(*(const uint4*)(zr + 1184 + qd * 16 + 8), f + 8);
; #pragma unroll
;             for (int i = 0; i < 16; ++i) ak[i] += cw[j * 160 + 64 + qd * 16 + i] * f[i];
;             unpack8(*(const uint4*)(zr + 1696 + eb * 32 + qd * 8), f);
; #pragma unroll
;             for (int i = 0; i < 8; ++i) av[i] += cw[j * 160 + 128 + qd * 8 + i] * f[i];
;           }
	v_pk_fma_f32 v[22:23], v[92:93], v[54:55], v[22:23]
	v_pk_fma_f32 v[20:21], v[94:95], v[56:57], v[20:21]
	s_waitcnt lgkmcnt(6)
	v_pk_fma_f32 v[18:19], v[98:99], v[64:65], v[18:19]
	v_pk_fma_f32 v[16:17], v[100:101], v[66:67], v[16:17]
	ds_read_b128 v[92:95], v74 offset:51328
	ds_read_b128 v[98:101], v74 offset:51344
	s_waitcnt vmcnt(9)
	v_lshlrev_b32_e32 v54, 16, v248
	v_and_b32_e32 v55, 0xffff0000, v248
	v_lshlrev_b32_e32 v56, 16, v249
	v_and_b32_e32 v57, 0xffff0000, v249
	v_lshlrev_b32_e32 v64, 16, v250
	v_and_b32_e32 v65, 0xffff0000, v250
	v_lshlrev_b32_e32 v66, 16, v251
	v_and_b32_e32 v67, 0xffff0000, v251
	global_load_dwordx4 v[248:251], v59, s[38:39] offset:1360
	s_waitcnt lgkmcnt(7)
	v_pk_fma_f32 v[14:15], v[102:103], v[54:55], v[14:15]
	v_pk_fma_f32 v[12:13], v[104:105], v[56:57], v[12:13]
	s_waitcnt lgkmcnt(6)
	v_pk_fma_f32 v[10:11], v[106:107], v[64:65], v[10:11]
	v_pk_fma_f32 v[8:9], v[108:109], v[66:67], v[8:9]
	ds_read_b128 v[102:105], v70 offset:51456
	ds_read_b128 v[106:109], v70 offset:51472
	s_waitcnt vmcnt(9)
	v_lshlrev_b32_e32 v54, 16, v252
	v_and_b32_e32 v55, 0xffff0000, v252
	v_lshlrev_b32_e32 v56, 16, v253
	v_and_b32_e32 v57, 0xffff0000, v253
	v_lshlrev_b32_e32 v64, 16, v254
	v_and_b32_e32 v65, 0xffff0000, v254
	v_lshlrev_b32_e32 v66, 16, v255
	v_and_b32_e32 v67, 0xffff0000, v255
	global_load_dwordx4 v[252:255], v59, s[38:39] offset:2368
	s_waitcnt lgkmcnt(7)
	v_pk_fma_f32 v[38:39], v[120:121], v[54:55], v[38:39]
	v_pk_fma_f32 v[36:37], v[122:123], v[56:57], v[36:37]
	s_waitcnt lgkmcnt(6)
	v_pk_fma_f32 v[34:35], v[60:61], v[64:65], v[34:35]
	v_pk_fma_f32 v[32:33], v[62:63], v[66:67], v[32:33]
	ds_read_b128 v[120:123], v70 offset:51488
	ds_read_b128 v[60:63], v70 offset:51504
	s_waitcnt vmcnt(9)
	v_lshlrev_b32_e32 v54, 16, v124
	v_and_b32_e32 v55, 0xffff0000, v124
	v_lshlrev_b32_e32 v56, 16, v125
	v_and_b32_e32 v57, 0xffff0000, v125
	v_lshlrev_b32_e32 v64, 16, v126
	v_and_b32_e32 v65, 0xffff0000, v126
	v_lshlrev_b32_e32 v66, 16, v127
	v_and_b32_e32 v67, 0xffff0000, v127
	global_load_dwordx4 v[124:127], v59, s[38:39] offset:2384
	s_waitcnt lgkmcnt(7)
	v_pk_fma_f32 v[30:31], v[84:85], v[54:55], v[30:31]
	v_pk_fma_f32 v[28:29], v[86:87], v[56:57], v[28:29]
	s_waitcnt lgkmcnt(6)
	v_pk_fma_f32 v[26:27], v[88:89], v[64:65], v[26:27]
	v_pk_fma_f32 v[24:25], v[90:91], v[66:67], v[24:25]
	ds_read_b128 v[84:87], v70 offset:51712
	ds_read_b128 v[88:91], v70 offset:51728
	s_waitcnt vmcnt(9)
	v_lshlrev_b32_e32 v54, 16, v128
	v_and_b32_e32 v55, 0xffff0000, v128
	v_lshlrev_b32_e32 v56, 16, v129
	v_and_b32_e32 v57, 0xffff0000, v129
	v_lshlrev_b32_e32 v64, 16, v130
	v_and_b32_e32 v65, 0xffff0000, v130
	v_lshlrev_b32_e32 v66, 16, v131
	v_and_b32_e32 v67, 0xffff0000, v131
	global_load_dwordx4 v[128:131], v97, s[38:39] offset:3392
	s_waitcnt lgkmcnt(7)
	v_pk_fma_f32 v[46:47], v[92:93], v[54:55], v[46:47]
	v_pk_fma_f32 v[40:41], v[94:95], v[56:57], v[40:41]
	s_waitcnt lgkmcnt(6)
	v_pk_fma_f32 v[42:43], v[98:99], v[64:65], v[42:43]
	v_pk_fma_f32 v[44:45], v[100:101], v[66:67], v[44:45]
	v_add_u32_e32 v59, 2, v58
	v_mad_u32_u24 v97, v59, s7, v155
	v_mad_u32_u24 v59, v59, s7, v154
	ds_read_b128 v[92:95], v70 offset:51744
	ds_read_b128 v[98:101], v70 offset:51760
	s_waitcnt vmcnt(9)
	v_lshlrev_b32_e32 v54, 16, v224
	v_and_b32_e32 v55, 0xffff0000, v224
	v_lshlrev_b32_e32 v56, 16, v225
	v_and_b32_e32 v57, 0xffff0000, v225
	v_lshlrev_b32_e32 v64, 16, v226
	v_and_b32_e32 v65, 0xffff0000, v226
	v_lshlrev_b32_e32 v66, 16, v227
	v_and_b32_e32 v67, 0xffff0000, v227
	global_load_dwordx4 v[224:227], v59, s[38:39] offset:1344
	s_waitcnt lgkmcnt(7)
	v_pk_fma_f32 v[22:23], v[102:103], v[54:55], v[22:23]
	v_pk_fma_f32 v[20:21], v[104:105], v[56:57], v[20:21]
	s_waitcnt lgkmcnt(6)
	v_pk_fma_f32 v[18:19], v[106:107], v[64:65], v[18:19]
	v_pk_fma_f32 v[16:17], v[108:109], v[66:67], v[16:17]
	ds_read_b128 v[102:105], v74 offset:51968
	ds_read_b128 v[106:109], v74 offset:51984
	s_waitcnt vmcnt(9)
	v_lshlrev_b32_e32 v54, 16, v228
	v_and_b32_e32 v55, 0xffff0000, v228
	v_lshlrev_b32_e32 v56, 16, v229
	v_and_b32_e32 v57, 0xffff0000, v229
	v_lshlrev_b32_e32 v64, 16, v230
	v_and_b32_e32 v65, 0xffff0000, v230
	v_lshlrev_b32_e32 v66, 16, v231
	v_and_b32_e32 v67, 0xffff0000, v231
	global_load_dwordx4 v[228:231], v59, s[38:39] offset:1360
	s_waitcnt lgkmcnt(7)
	v_pk_fma_f32 v[14:15], v[120:121], v[54:55], v[14:15]
	v_pk_fma_f32 v[12:13], v[122:123], v[56:57], v[12:13]
	s_waitcnt lgkmcnt(6)
	v_pk_fma_f32 v[10:11], v[60:61], v[64:65], v[10:11]
	v_pk_fma_f32 v[8:9], v[62:63], v[66:67], v[8:9]
	ds_read_b128 v[120:123], v70 offset:52096
	ds_read_b128 v[60:63], v70 offset:52112
	s_waitcnt vmcnt(9)
	v_lshlrev_b32_e32 v54, 16, v232
	v_and_b32_e32 v55, 0xffff0000, v232
	v_lshlrev_b32_e32 v56, 16, v233
	v_and_b32_e32 v57, 0xffff0000, v233
	v_lshlrev_b32_e32 v64, 16, v234
	v_and_b32_e32 v65, 0xffff0000, v234
	v_lshlrev_b32_e32 v66, 16, v235
	v_and_b32_e32 v67, 0xffff0000, v235
	global_load_dwordx4 v[232:235], v59, s[38:39] offset:2368
	s_waitcnt lgkmcnt(7)
	v_pk_fma_f32 v[38:39], v[84:85], v[54:55], v[38:39]
	v_pk_fma_f32 v[36:37], v[86:87], v[56:57], v[36:37]
	s_waitcnt lgkmcnt(6)
	v_pk_fma_f32 v[34:35], v[88:89], v[64:65], v[34:35]
	v_pk_fma_f32 v[32:33], v[90:91], v[66:67], v[32:33]
	ds_read_b128 v[84:87], v70 offset:52128
	ds_read_b128 v[88:91], v70 offset:52144
	s_waitcnt vmcnt(9)
	v_lshlrev_b32_e32 v54, 16, v236
	v_and_b32_e32 v55, 0xffff0000, v236
	v_lshlrev_b32_e32 v56, 16, v237
	v_and_b32_e32 v57, 0xffff0000, v237
	v_lshlrev_b32_e32 v64, 16, v238
	v_and_b32_e32 v65, 0xffff0000, v238
	v_lshlrev_b32_e32 v66, 16, v239
	v_and_b32_e32 v67, 0xffff0000, v239
	global_load_dwordx4 v[236:239], v59, s[38:39] offset:2384
	s_waitcnt lgkmcnt(7)
; DI void gdn_chain(const P& p, int cid, char* smem) {
;     ...
;         for (int j = 0; j < 5; ++j) {
;           const int tt = tau + j - 2;
;           if (tt >= 0 && tt < len) {
;             const u16* zr = z + (size_t)(base + tt) * EVEN_IN + h * 64;
;             float f[16];
;             unpack8(*(const uint4*)(zr + 672 + qd * 16), f); unpack8(*(const uint4*)(zr + 672 + qd * 16 + 8), f + 8);
; #pragma unroll
;             for (int i = 0; i < 16; ++i) aq[i] += cw[j * 160 + qd * 16 + i] * f[i];
;             unpack8(*(const uint4*)(zr + 1184 + qd * 16), f); unpack8(*(const uint4*)(zr + 1184 + qd * 16 + 8), f + 8);
; #pragma unroll
;             for (int i = 0; i < 16; ++i) ak[i] += cw[j * 160 + 64 + qd * 16 + i] * f[i];
;             unpack8(*(const uint4*)(zr + 1696 + eb * 32 + qd * 8), f);
; #pragma unroll
;             for (int i = 0; i < 8; ++i) av[i] += cw[j * 160 + 128 + qd * 8 + i] * f[i];
	v_pk_fma_f32 v[30:31], v[92:93], v[54:55], v[30:31]
	v_pk_fma_f32 v[28:29], v[94:95], v[56:57], v[28:29]
	s_waitcnt lgkmcnt(6)
	v_pk_fma_f32 v[26:27], v[98:99], v[64:65], v[26:27]
	v_pk_fma_f32 v[24:25], v[100:101], v[66:67], v[24:25]
	ds_read_b128 v[92:95], v70 offset:52352
	ds_read_b128 v[98:101], v70 offset:52368
	s_waitcnt vmcnt(9)
	v_lshlrev_b32_e32 v54, 16, v240
	v_and_b32_e32 v55, 0xffff0000, v240
	v_lshlrev_b32_e32 v56, 16, v241
	v_and_b32_e32 v57, 0xffff0000, v241
	v_lshlrev_b32_e32 v64, 16, v242
	v_and_b32_e32 v65, 0xffff0000, v242
	v_lshlrev_b32_e32 v66, 16, v243
	v_and_b32_e32 v67, 0xffff0000, v243
	global_load_dwordx4 v[240:243], v97, s[38:39] offset:3392
	s_waitcnt lgkmcnt(7)
	v_pk_fma_f32 v[46:47], v[102:103], v[54:55], v[46:47]
	v_pk_fma_f32 v[40:41], v[104:105], v[56:57], v[40:41]
	s_waitcnt lgkmcnt(6)
	v_pk_fma_f32 v[42:43], v[106:107], v[64:65], v[42:43]
	v_pk_fma_f32 v[44:45], v[108:109], v[66:67], v[44:45]
	ds_read_b128 v[102:105], v70 offset:52384
	ds_read_b128 v[106:109], v70 offset:52400
	s_waitcnt vmcnt(9)
	v_lshlrev_b32_e32 v54, 16, v244
	v_and_b32_e32 v55, 0xffff0000, v244
	v_lshlrev_b32_e32 v56, 16, v245
	v_and_b32_e32 v57, 0xffff0000, v245
	v_lshlrev_b32_e32 v64, 16, v246
	v_and_b32_e32 v65, 0xffff0000, v246
	v_lshlrev_b32_e32 v66, 16, v247
	v_and_b32_e32 v67, 0xffff0000, v247
	s_waitcnt lgkmcnt(7)
	v_pk_fma_f32 v[22:23], v[120:121], v[54:55], v[22:23]
	v_pk_fma_f32 v[20:21], v[122:123], v[56:57], v[20:21]
	s_waitcnt lgkmcnt(6)
	v_pk_fma_f32 v[18:19], v[60:61], v[64:65], v[18:19]
	v_pk_fma_f32 v[16:17], v[62:63], v[66:67], v[16:17]
	ds_read_b128 v[120:123], v74 offset:52608
	ds_read_b128 v[60:63], v74 offset:52624
	s_waitcnt vmcnt(8)
	v_lshlrev_b32_e32 v54, 16, v248
	v_and_b32_e32 v55, 0xffff0000, v248
	v_lshlrev_b32_e32 v56, 16, v249
	v_and_b32_e32 v57, 0xffff0000, v249
	v_lshlrev_b32_e32 v64, 16, v250
	v_and_b32_e32 v65, 0xffff0000, v250
	v_lshlrev_b32_e32 v66, 16, v251
	v_and_b32_e32 v67, 0xffff0000, v251
	s_waitcnt lgkmcnt(7)
	v_pk_fma_f32 v[14:15], v[84:85], v[54:55], v[14:15]
	v_pk_fma_f32 v[12:13], v[86:87], v[56:57], v[12:13]
	s_waitcnt lgkmcnt(6)
	v_pk_fma_f32 v[10:11], v[88:89], v[64:65], v[10:11]
	v_pk_fma_f32 v[8:9], v[90:91], v[66:67], v[8:9]
	ds_read_b128 v[84:87], v70 offset:52736
	ds_read_b128 v[88:91], v70 offset:52752
	s_waitcnt vmcnt(7)
	v_lshlrev_b32_e32 v54, 16, v252
	v_and_b32_e32 v55, 0xffff0000, v252
	v_lshlrev_b32_e32 v56, 16, v253
	v_and_b32_e32 v57, 0xffff0000, v253
	v_lshlrev_b32_e32 v64, 16, v254
	v_and_b32_e32 v65, 0xffff0000, v254
	v_lshlrev_b32_e32 v66, 16, v255
	v_and_b32_e32 v67, 0xffff0000, v255
	s_waitcnt lgkmcnt(7)
	v_pk_fma_f32 v[38:39], v[92:93], v[54:55], v[38:39]
	v_pk_fma_f32 v[36:37], v[94:95], v[56:57], v[36:37]
	s_waitcnt lgkmcnt(6)
	v_pk_fma_f32 v[34:35], v[98:99], v[64:65], v[34:35]
	v_pk_fma_f32 v[32:33], v[100:101], v[66:67], v[32:33]
	ds_read_b128 v[92:95], v70 offset:52768
	ds_read_b128 v[98:101], v70 offset:52784
	s_waitcnt vmcnt(6)
	v_lshlrev_b32_e32 v54, 16, v124
	v_and_b32_e32 v55, 0xffff0000, v124
	v_lshlrev_b32_e32 v56, 16, v125
	v_and_b32_e32 v57, 0xffff0000, v125
	v_lshlrev_b32_e32 v64, 16, v126
	v_and_b32_e32 v65, 0xffff0000, v126
	v_lshlrev_b32_e32 v66, 16, v127
	v_and_b32_e32 v67, 0xffff0000, v127
	s_waitcnt lgkmcnt(7)
	v_pk_fma_f32 v[30:31], v[102:103], v[54:55], v[30:31]
	v_pk_fma_f32 v[28:29], v[104:105], v[56:57], v[28:29]
	s_waitcnt lgkmcnt(6)
	v_pk_fma_f32 v[26:27], v[106:107], v[64:65], v[26:27]
	v_pk_fma_f32 v[24:25], v[108:109], v[66:67], v[24:25]
	ds_read_b128 v[102:105], v70 offset:52992
	ds_read_b128 v[106:109], v70 offset:53008
	s_waitcnt vmcnt(5)
; DI void gdn_chain(const P& p, int cid, char* smem) {
;     ...
;         for (int j = 0; j < 5; ++j) {
;           const int tt = tau + j - 2;
;           if (tt >= 0 && tt < len) {
;             const u16* zr = z + (size_t)(base + tt) * EVEN_IN + h * 64;
;             float f[16];
;             unpack8(*(const uint4*)(zr + 672 + qd * 16), f); unpack8(*(const uint4*)(zr + 672 + qd * 16 + 8), f + 8);
; #pragma unroll
;             for (int i = 0; i < 16; ++i) aq[i] += cw[j * 160 + qd * 16 + i] * f[i];
;             unpack8(*(const uint4*)(zr + 1184 + qd * 16), f); unpack8(*(const uint4*)(zr + 1184 + qd * 16 + 8), f + 8);
; #pragma unroll
;             for (int i = 0; i < 16; ++i) ak[i] += cw[j * 160 + 64 + qd * 16 + i] * f[i];
;             unpack8(*(const uint4*)(zr + 1696 + eb * 32 + qd * 8), f);
; #pragma unroll
;             for (int i = 0; i < 8; ++i) av[i] += cw[j * 160 + 128 + qd * 8 + i] * f[i];
	v_lshlrev_b32_e32 v54, 16, v128
	v_and_b32_e32 v55, 0xffff0000, v128
	v_lshlrev_b32_e32 v56, 16, v129
	v_and_b32_e32 v57, 0xffff0000, v129
	v_lshlrev_b32_e32 v64, 16, v130
	v_and_b32_e32 v65, 0xffff0000, v130
	v_lshlrev_b32_e32 v66, 16, v131
	v_and_b32_e32 v67, 0xffff0000, v131
	s_waitcnt lgkmcnt(7)
	v_pk_fma_f32 v[46:47], v[120:121], v[54:55], v[46:47]
	v_pk_fma_f32 v[40:41], v[122:123], v[56:57], v[40:41]
	s_waitcnt lgkmcnt(6)
	v_pk_fma_f32 v[42:43], v[60:61], v[64:65], v[42:43]
	v_pk_fma_f32 v[44:45], v[62:63], v[66:67], v[44:45]
	ds_read_b128 v[120:123], v70 offset:53024
	ds_read_b128 v[60:63], v70 offset:53040
	s_waitcnt vmcnt(4)
	v_lshlrev_b32_e32 v54, 16, v224
	v_and_b32_e32 v55, 0xffff0000, v224
	v_lshlrev_b32_e32 v56, 16, v225
	v_and_b32_e32 v57, 0xffff0000, v225
	v_lshlrev_b32_e32 v64, 16, v226
	v_and_b32_e32 v65, 0xffff0000, v226
	v_lshlrev_b32_e32 v66, 16, v227
	v_and_b32_e32 v67, 0xffff0000, v227
	s_waitcnt lgkmcnt(7)
	v_pk_fma_f32 v[22:23], v[84:85], v[54:55], v[22:23]
	v_pk_fma_f32 v[20:21], v[86:87], v[56:57], v[20:21]
	s_waitcnt lgkmcnt(6)
	v_pk_fma_f32 v[18:19], v[88:89], v[64:65], v[18:19]
	v_pk_fma_f32 v[16:17], v[90:91], v[66:67], v[16:17]
	ds_read_b128 v[84:87], v74 offset:53248
	ds_read_b128 v[88:91], v74 offset:53264
	s_waitcnt vmcnt(3)
	v_lshlrev_b32_e32 v54, 16, v228
	v_and_b32_e32 v55, 0xffff0000, v228
	v_lshlrev_b32_e32 v56, 16, v229
	v_and_b32_e32 v57, 0xffff0000, v229
	v_lshlrev_b32_e32 v64, 16, v230
	v_and_b32_e32 v65, 0xffff0000, v230
	v_lshlrev_b32_e32 v66, 16, v231
	v_and_b32_e32 v67, 0xffff0000, v231
	s_waitcnt lgkmcnt(7)
	v_pk_fma_f32 v[14:15], v[92:93], v[54:55], v[14:15]
	v_pk_fma_f32 v[12:13], v[94:95], v[56:57], v[12:13]
	s_waitcnt lgkmcnt(6)
	v_pk_fma_f32 v[10:11], v[98:99], v[64:65], v[10:11]
	v_pk_fma_f32 v[8:9], v[100:101], v[66:67], v[8:9]
	s_waitcnt vmcnt(2)
	v_lshlrev_b32_e32 v54, 16, v232
	v_and_b32_e32 v55, 0xffff0000, v232
	v_lshlrev_b32_e32 v56, 16, v233
	v_and_b32_e32 v57, 0xffff0000, v233
	v_lshlrev_b32_e32 v64, 16, v234
	v_and_b32_e32 v65, 0xffff0000, v234
	v_lshlrev_b32_e32 v66, 16, v235
	v_and_b32_e32 v67, 0xffff0000, v235
	s_waitcnt lgkmcnt(5)
	v_pk_fma_f32 v[38:39], v[102:103], v[54:55], v[38:39]
	v_pk_fma_f32 v[36:37], v[104:105], v[56:57], v[36:37]
	s_waitcnt lgkmcnt(4)
	v_pk_fma_f32 v[34:35], v[106:107], v[64:65], v[34:35]
	v_pk_fma_f32 v[32:33], v[108:109], v[66:67], v[32:33]
	s_waitcnt vmcnt(1)
	v_lshlrev_b32_e32 v54, 16, v236
	v_and_b32_e32 v55, 0xffff0000, v236
	v_lshlrev_b32_e32 v56, 16, v237
	v_and_b32_e32 v57, 0xffff0000, v237
	v_lshlrev_b32_e32 v64, 16, v238
	v_and_b32_e32 v65, 0xffff0000, v238
	v_lshlrev_b32_e32 v66, 16, v239
	v_and_b32_e32 v67, 0xffff0000, v239
	s_waitcnt lgkmcnt(3)
	v_pk_fma_f32 v[30:31], v[120:121], v[54:55], v[30:31]
	v_pk_fma_f32 v[28:29], v[122:123], v[56:57], v[28:29]
	s_waitcnt lgkmcnt(2)
	v_pk_fma_f32 v[26:27], v[60:61], v[64:65], v[26:27]
	v_pk_fma_f32 v[24:25], v[62:63], v[66:67], v[24:25]
	s_waitcnt vmcnt(0)
	v_lshlrev_b32_e32 v54, 16, v240
	v_and_b32_e32 v55, 0xffff0000, v240
	v_lshlrev_b32_e32 v56, 16, v241
	v_and_b32_e32 v57, 0xffff0000, v241
	v_lshlrev_b32_e32 v64, 16, v242
	v_and_b32_e32 v65, 0xffff0000, v242
	v_lshlrev_b32_e32 v66, 16, v243
	v_and_b32_e32 v67, 0xffff0000, v243
	s_waitcnt lgkmcnt(1)
	v_pk_fma_f32 v[46:47], v[84:85], v[54:55], v[46:47]
	v_pk_fma_f32 v[40:41], v[86:87], v[56:57], v[40:41]
	s_waitcnt lgkmcnt(0)
	v_pk_fma_f32 v[42:43], v[88:89], v[64:65], v[42:43]
	v_pk_fma_f32 v[44:45], v[90:91], v[66:67], v[44:45]
	s_branch .Lgdn_conv_done

; DI float silu_f(float x) { return x * __builtin_amdgcn_rcpf(1.f + __expf(-x)); }
; DI void gdn_chain(const P& p, int cid, char* smem) {
;     ...
;         float sq2 = 0.f, sk2 = 0.f;
; #pragma unroll
;         for (int i = 0; i < 16; ++i) {
;           aq[i] = silu_f(aq[i]); ak[i] = silu_f(ak[i]);
;           sq2 += aq[i] * aq[i]; sk2 += ak[i] * ak[i];
;         }
;     ...
;         *(float4*)(vs + pp * 32 + qd * 8) = make_float4(silu_f(av[0]), silu_f(av[1]), silu_f(av[2]), silu_f(av[3]));
.Lgdn_conv_done:
	v_mul_f32_e32 v55, 0xbfb8aa3b, v38
	v_mul_f32_e32 v56, 0xbfb8aa3b, v23
	v_exp_f32_e32 v55, v55
	v_exp_f32_e32 v57, v56
	v_mul_f32_e32 v56, 0xbfb8aa3b, v39
	v_exp_f32_e32 v59, v56
	v_add_f32_e32 v55, 1.0, v55
	v_rcp_f32_e32 v56, v55
	v_add_f32_e32 v55, 1.0, v57
	v_add_f32_e32 v57, 1.0, v59
	v_mul_f32_e32 v59, 0xbfb8aa3b, v20
	v_exp_f32_e32 v59, v59
	v_mul_f32_e32 v60, 0xbfb8aa3b, v36
	v_exp_f32_e32 v61, v60
	v_mul_f32_e32 v62, 0xbfb8aa3b, v37
	v_add_f32_e32 v59, 1.0, v59
	v_rcp_f32_e32 v60, v59
	v_add_f32_e32 v59, 1.0, v61
	v_mul_f32_e32 v61, 0xbfb8aa3b, v21
	v_exp_f32_e32 v61, v61
	v_exp_f32_e32 v63, v62
	v_rcp_f32_e32 v62, v59
	v_mul_f32_e32 v66, 0xbfb8aa3b, v35
	v_add_f32_e32 v59, 1.0, v61
	v_rcp_f32_e32 v61, v59
	v_add_f32_e32 v59, 1.0, v63
	v_mul_f32_e32 v63, 0xbfb8aa3b, v18
	v_exp_f32_e32 v64, v63
	v_mul_f32_e32 v63, 0xbfb8aa3b, v34
	v_exp_f32_e32 v65, v63
	v_rcp_f32_e32 v63, v59
	v_add_f32_e32 v59, 1.0, v64
	v_rcp_f32_e32 v64, v59
	v_add_f32_e32 v59, 1.0, v65
	v_mul_f32_e32 v65, 0xbfb8aa3b, v19
	v_exp_f32_e32 v65, v65
	v_exp_f32_e32 v67, v66
	v_rcp_f32_e32 v66, v59
	v_mul_f32_e32 v54, 0xbfb8aa3b, v22
	v_add_f32_e32 v59, 1.0, v65
	v_rcp_f32_e32 v65, v59
	v_add_f32_e32 v59, 1.0, v67
	v_mul_f32_e32 v67, 0xbfb8aa3b, v16
	v_exp_f32_e32 v83, v67
	v_mul_f32_e32 v67, 0xbfb8aa3b, v32
	v_exp_f32_e32 v85, v67
	v_rcp_f32_e32 v67, v59
	v_add_f32_e32 v59, 1.0, v83
	v_mul_f32_e32 v83, 0xbfb8aa3b, v17
	v_rcp_f32_e32 v84, v59
	v_add_f32_e32 v59, 1.0, v85
	v_exp_f32_e32 v83, v83
	v_mul_f32_e32 v85, 0xbfb8aa3b, v33
	v_exp_f32_e32 v87, v85
	v_rcp_f32_e32 v86, v59
	v_add_f32_e32 v59, 1.0, v83
	v_mul_f32_e32 v83, 0xbfb8aa3b, v14
	v_rcp_f32_e32 v85, v59
	v_add_f32_e32 v59, 1.0, v87
	v_exp_f32_e32 v83, v83
	v_mul_f32_e32 v87, 0xbfb8aa3b, v30
	v_exp_f32_e32 v89, v87
	v_rcp_f32_e32 v87, v59
	v_add_f32_e32 v59, 1.0, v83
	v_mul_f32_e32 v83, 0xbfb8aa3b, v15
	v_rcp_f32_e32 v88, v59
	v_add_f32_e32 v59, 1.0, v89
	v_exp_f32_e32 v83, v83
	v_mul_f32_e32 v89, 0xbfb8aa3b, v31
	v_exp_f32_e32 v91, v89
	v_rcp_f32_e32 v90, v59
	v_add_f32_e32 v59, 1.0, v83
	v_mul_f32_e32 v83, 0xbfb8aa3b, v12
	v_rcp_f32_e32 v89, v59
	v_add_f32_e32 v59, 1.0, v91
	v_exp_f32_e32 v83, v83
	v_mul_f32_e32 v91, 0xbfb8aa3b, v28
	v_exp_f32_e32 v93, v91
	v_rcp_f32_e32 v91, v59
	v_add_f32_e32 v59, 1.0, v83
	v_mul_f32_e32 v83, 0xbfb8aa3b, v13
	v_rcp_f32_e32 v92, v59
	v_add_f32_e32 v59, 1.0, v93
	v_exp_f32_e32 v83, v83
	v_mul_f32_e32 v93, 0xbfb8aa3b, v29
	v_exp_f32_e32 v95, v93
	v_rcp_f32_e32 v94, v59
	v_add_f32_e32 v59, 1.0, v83
	v_mul_f32_e32 v83, 0xbfb8aa3b, v10
	v_rcp_f32_e32 v93, v59
	v_add_f32_e32 v59, 1.0, v95
	v_exp_f32_e32 v83, v83
	v_mul_f32_e32 v95, 0xbfb8aa3b, v26
	v_exp_f32_e32 v97, v95
	v_exp_f32_e32 v54, v54
	v_rcp_f32_e32 v95, v59
	v_add_f32_e32 v59, 1.0, v83
	v_mul_f32_e32 v83, 0xbfb8aa3b, v11
	v_rcp_f32_e32 v98, v59
	v_add_f32_e32 v59, 1.0, v97
	v_exp_f32_e32 v83, v83
	v_mul_f32_e32 v97, 0xbfb8aa3b, v27
	v_add_f32_e32 v54, 1.0, v54
	v_exp_f32_e32 v97, v97
	v_rcp_f32_e32 v54, v54
	v_rcp_f32_e32 v55, v55
	v_rcp_f32_e32 v57, v57
	v_rcp_f32_e32 v100, v59
	v_add_f32_e32 v59, 1.0, v83
	v_mul_f32_e32 v83, 0xbfb8aa3b, v8
	v_rcp_f32_e32 v99, v59
	v_add_f32_e32 v59, 1.0, v97
	v_exp_f32_e32 v83, v83
	v_mul_f32_e32 v97, 0xbfb8aa3b, v24
	v_exp_f32_e32 v97, v97
	v_pk_mul_f32 v[22:23], v[22:23], v[54:55]
	v_pk_mul_f32 v[38:39], v[38:39], v[56:57]
	v_pk_mul_f32 v[20:21], v[20:21], v[60:61]
	v_mov_b32_e32 v60, v38
	v_mov_b32_e32 v61, v22
	v_pk_mul_f32 v[36:37], v[36:37], v[62:63]
	v_pk_mul_f32 v[60:61], v[60:61], v[60:61]
	v_mov_b32_e32 v62, v39
	v_mov_b32_e32 v63, v23
	v_rcp_f32_e32 v101, v59
	v_add_f32_e32 v59, 1.0, v83
	v_mul_f32_e32 v83, 0xbfb8aa3b, v9
	v_pk_fma_f32 v[60:61], v[62:63], v[62:63], v[60:61]
	v_mov_b32_e32 v62, v36
	v_mov_b32_e32 v63, v20
	v_rcp_f32_e32 v102, v59
	v_add_f32_e32 v59, 1.0, v97
	v_exp_f32_e32 v83, v83
	v_mul_f32_e32 v97, 0xbfb8aa3b, v25
	v_pk_mul_f32 v[18:19], v[18:19], v[64:65]
	v_pk_mul_f32 v[34:35], v[34:35], v[66:67]
	v_mov_b32_e32 v64, v37
	v_mov_b32_e32 v65, v21
	v_pk_fma_f32 v[60:61], v[62:63], v[62:63], v[60:61]
	v_exp_f32_e32 v97, v97
	v_pk_mul_f32 v[16:17], v[16:17], v[84:85]
	v_pk_mul_f32 v[32:33], v[32:33], v[86:87]
	v_pk_fma_f32 v[60:61], v[64:65], v[64:65], v[60:61]
	v_mov_b32_e32 v62, v34
	v_mov_b32_e32 v63, v18
	v_pk_mul_f32 v[54:55], v[16:17], v[16:17]
	v_pk_mul_f32 v[56:57], v[32:33], v[32:33]
	v_mov_b32_e32 v64, v35
	v_mov_b32_e32 v65, v19
	v_pk_fma_f32 v[60:61], v[62:63], v[62:63], v[60:61]
	v_mov_b32_e32 v62, v56
	v_pk_fma_f32 v[60:61], v[64:65], v[64:65], v[60:61]
	v_mov_b32_e32 v63, v54
	v_rcp_f32_e32 v104, v59
	v_add_f32_e32 v59, 1.0, v83
	v_pk_add_f32 v[60:61], v[62:63], v[60:61]
	v_mov_b32_e32 v54, v57
	v_pk_mul_f32 v[56:57], v[14:15], v[88:89]
	v_pk_mul_f32 v[62:63], v[30:31], v[90:91]
	v_rcp_f32_e32 v103, v59
	v_add_f32_e32 v59, 1.0, v97
	v_pk_mul_f32 v[14:15], v[56:57], v[56:57]
	v_pk_mul_f32 v[30:31], v[62:63], v[62:63]
	v_rcp_f32_e32 v105, v59
	v_pk_add_f32 v[54:55], v[54:55], v[60:61]
	v_pk_mul_f32 v[60:61], v[12:13], v[92:93]
	v_pk_mul_f32 v[64:65], v[28:29], v[94:95]
	v_mov_b32_e32 v90, v30
	v_mov_b32_e32 v91, v14
	v_pk_mul_f32 v[12:13], v[60:61], v[60:61]
	v_pk_mul_f32 v[28:29], v[64:65], v[64:65]
	v_pk_add_f32 v[54:55], v[90:91], v[54:55]
	v_mov_b32_e32 v14, v31
	v_pk_mul_f32 v[66:67], v[10:11], v[98:99]
	v_pk_mul_f32 v[86:87], v[26:27], v[100:101]
	v_pk_add_f32 v[14:15], v[14:15], v[54:55]
	v_mov_b32_e32 v30, v28
	v_mov_b32_e32 v31, v12
	v_pk_mul_f32 v[10:11], v[66:67], v[66:67]
	v_pk_mul_f32 v[26:27], v[86:87], v[86:87]
	v_pk_add_f32 v[14:15], v[30:31], v[14:15]
	v_mov_b32_e32 v12, v29
	v_pk_mul_f32 v[84:85], v[8:9], v[102:103]
; DI float silu_f(float x) { return x * __builtin_amdgcn_rcpf(1.f + __expf(-x)); }
; DI void gdn_chain(const P& p, int cid, char* smem) {
;     ...
;         sq2 = quad_sum(sq2);
;         sk2 = quad_sum(sk2);
;         const float rq = rsqrtf(sq2 + EPS) * 0.125f, rk = rsqrtf(sk2 + EPS);
; #pragma unroll
;         for (int i = 0; i < 16; ++i) { aq[i] *= rq; ak[i] *= rk; }
; #pragma unroll
;         for (int i = 0; i < 4; ++i) {
;           *(float4*)(qs + pp * 64 + qd * 16 + i * 4) = make_float4(aq[4 * i], aq[4 * i + 1], aq[4 * i + 2], aq[4 * i + 3]);
;           *(float4*)(ks + pp * 64 + qd * 16 + i * 4) = make_float4(ak[4 * i], ak[4 * i + 1], ak[4 * i + 2], ak[4 * i + 3]);
;         }
;         *(float4*)(vs + pp * 32 + qd * 8) = make_float4(silu_f(av[0]), silu_f(av[1]), silu_f(av[2]), silu_f(av[3]));
;         *(float4*)(vs + pp * 32 + qd * 8 + 4) = make_float4(silu_f(av[4]), silu_f(av[5]), silu_f(av[6]), silu_f(av[7]));
;         float gsame = 0.f, kk = 0.f, g21 = 0.f;
; #pragma unroll
;         for (int i = 0; i < 16; ++i) {
;           const float kp = __builtin_bit_cast(float, __builtin_amdgcn_mov_dpp(__builtin_bit_cast(int, ak[i]), 0x114, 0xF, 0xF, true));
;           gsame += aq[i] * ak[i];
;           kk += kp * ak[i];
;           g21 += aq[i] * kp;
;         }
	v_pk_mul_f32 v[88:89], v[24:25], v[104:105]
	v_pk_add_f32 v[12:13], v[12:13], v[14:15]
	v_mov_b32_e32 v14, v26
	v_mov_b32_e32 v15, v10
	v_pk_mul_f32 v[8:9], v[84:85], v[84:85]
	v_pk_mul_f32 v[24:25], v[88:89], v[88:89]
	v_pk_add_f32 v[12:13], v[14:15], v[12:13]
	v_mov_b32_e32 v10, v27
	v_pk_add_f32 v[10:11], v[10:11], v[12:13]
	v_mov_b32_e32 v12, v24
	v_mov_b32_e32 v13, v8
	v_pk_add_f32 v[10:11], v[12:13], v[10:11]
	v_mov_b32_e32 v8, v25
	v_pk_add_f32 v[8:9], v[8:9], v[10:11]
	v_mul_f32_e32 v59, 0xbfb8aa3b, v42
	v_exp_f32_e32 v59, v59
	v_mov_b32_dpp v11, v9 quad_perm:[1,0,3,2] row_mask:0xf bank_mask:0xf bound_ctrl:1
	v_mov_b32_dpp v10, v8 quad_perm:[1,0,3,2] row_mask:0xf bank_mask:0xf bound_ctrl:1
	v_pk_add_f32 v[8:9], v[8:9], v[10:11]
	s_nop 1
	v_mov_b32_dpp v11, v9 quad_perm:[2,3,0,1] row_mask:0xf bank_mask:0xf bound_ctrl:1
	v_mov_b32_dpp v10, v8 quad_perm:[2,3,0,1] row_mask:0xf bank_mask:0xf bound_ctrl:1
	v_pk_add_f32 v[8:9], v[8:9], v[10:11]
	s_nop 0
	v_pk_add_f32 v[24:25], v[8:9], s[2:3] op_sel_hi:[1,0]
	s_nop 0
	v_mul_f32_e32 v8, 0x4b800000, v25
	v_cmp_gt_f32_e32 vcc, s9, v25
	s_nop 1
	v_cndmask_b32_e32 v8, v25, v8, vcc
	v_rsq_f32_e32 v8, v8
	v_mul_f32_e32 v25, 0x4b800000, v24
	v_mul_f32_e32 v9, 0x45800000, v8
	v_cndmask_b32_e32 v8, v8, v9, vcc
	v_cmp_gt_f32_e32 vcc, s9, v24
	v_mul_f32_e32 v26, 0x3e000000, v8
	v_pk_mul_f32 v[8:9], v[22:23], v[26:27] op_sel_hi:[1,0]
	v_cndmask_b32_e32 v24, v24, v25, vcc
	v_rsq_f32_e32 v24, v24
	v_pk_mul_f32 v[10:11], v[20:21], v[26:27] op_sel_hi:[1,0]
	v_pk_mul_f32 v[12:13], v[18:19], v[26:27] op_sel_hi:[1,0]
	v_pk_mul_f32 v[14:15], v[16:17], v[26:27] op_sel_hi:[1,0]
	v_mul_f32_e32 v25, 0x45800000, v24
	v_cndmask_b32_e32 v54, v24, v25, vcc
	v_pk_mul_f32 v[16:17], v[56:57], v[26:27] op_sel_hi:[1,0]
	v_pk_mul_f32 v[18:19], v[60:61], v[26:27] op_sel_hi:[1,0]
	v_pk_mul_f32 v[20:21], v[66:67], v[26:27] op_sel_hi:[1,0]
	v_pk_mul_f32 v[22:23], v[84:85], v[26:27] op_sel_hi:[1,0]
	v_pk_mul_f32 v[24:25], v[38:39], v[54:55] op_sel_hi:[1,0]
	v_pk_mul_f32 v[26:27], v[36:37], v[54:55] op_sel_hi:[1,0]
	v_pk_mul_f32 v[28:29], v[34:35], v[54:55] op_sel_hi:[1,0]
	v_pk_mul_f32 v[30:31], v[32:33], v[54:55] op_sel_hi:[1,0]
	v_pk_mul_f32 v[32:33], v[62:63], v[54:55] op_sel_hi:[1,0]
	v_pk_mul_f32 v[34:35], v[64:65], v[54:55] op_sel_hi:[1,0]
	v_pk_mul_f32 v[36:37], v[86:87], v[54:55] op_sel_hi:[1,0]
	v_pk_mul_f32 v[38:39], v[88:89], v[54:55] op_sel_hi:[1,0]
	v_mul_f32_e32 v54, 0xbfb8aa3b, v46
	v_mul_f32_e32 v55, 0xbfb8aa3b, v47
	v_exp_f32_e32 v54, v54
	v_exp_f32_e32 v55, v55
	v_mul_f32_e32 v60, 0xbfb8aa3b, v43
	v_exp_f32_e32 v60, v60
	v_add_f32_e32 v54, 1.0, v54
	v_add_f32_e32 v55, 1.0, v55
	v_rcp_f32_e32 v54, v54
	v_rcp_f32_e32 v55, v55
	v_mul_f32_e32 v56, 0xbfb8aa3b, v40
	v_mul_f32_e32 v57, 0xbfb8aa3b, v41
	v_exp_f32_e32 v56, v56
	v_pk_mul_f32 v[54:55], v[46:47], v[54:55]
	v_add_f32_e32 v46, 1.0, v59
	v_mul_f32_e32 v59, 0xbfb8aa3b, v44
	v_add_f32_e32 v47, 1.0, v60
	v_exp_f32_e32 v59, v59
	v_mul_f32_e32 v60, 0xbfb8aa3b, v45
	v_exp_f32_e32 v57, v57
	v_exp_f32_e32 v61, v60
	v_add_f32_e32 v59, 1.0, v59
	v_add_f32_e32 v56, 1.0, v56
	v_add_f32_e32 v57, 1.0, v57
	v_rcp_f32_e32 v60, v59
	v_add_f32_e32 v59, 1.0, v61
	v_rcp_f32_e32 v56, v56
	v_rcp_f32_e32 v57, v57
	v_rcp_f32_e32 v46, v46
	v_rcp_f32_e32 v47, v47
	v_rcp_f32_e32 v61, v59
	v_pk_mul_f32 v[56:57], v[40:41], v[56:57]
	ds_write_b128 v71, v[8:11]
	v_pk_mul_f32 v[40:41], v[42:43], v[46:47]
	v_pk_mul_f32 v[42:43], v[44:45], v[60:61]
	ds_write_b128 v71, v[12:15] offset:16
	ds_write_b128 v71, v[16:19] offset:32
	ds_write_b128 v71, v[20:23] offset:48
	ds_write_b128 v71, v[24:27] offset:16384
	ds_write_b128 v71, v[28:31] offset:16400
	ds_write_b128 v71, v[32:35] offset:16416
	ds_write_b128 v71, v[36:39] offset:16432
	ds_write_b128 v79, v[40:43] offset:32784
	v_mov_b32_dpp v40, v24 row_shr:4 row_mask:0xf bank_mask:0xf bound_ctrl:1
	v_mov_b32_e32 v41, v24
	v_fma_f32 v59, v24, v40, 0
	v_mov_b32_dpp v42, v25 row_shr:4 row_mask:0xf bank_mask:0xf bound_ctrl:1
	v_pk_fma_f32 v[40:41], v[8:9], v[40:41], 0 op_sel_hi:[0,1,0]
	v_mov_b32_e32 v43, v25
	v_fmac_f32_e32 v59, v25, v42
	v_mov_b32_dpp v44, v26 row_shr:4 row_mask:0xf bank_mask:0xf bound_ctrl:1
	v_pk_fma_f32 v[8:9], v[8:9], v[42:43], v[40:41] op_sel:[1,0,0]
	v_mov_b32_e32 v45, v26
	v_fmac_f32_e32 v59, v26, v44
	v_mov_b32_dpp v46, v27 row_shr:4 row_mask:0xf bank_mask:0xf bound_ctrl:1
	v_pk_fma_f32 v[8:9], v[10:11], v[44:45], v[8:9] op_sel_hi:[0,1,1]
	v_mov_b32_e32 v47, v27
	ds_write_b128 v79, v[54:57] offset:32768
	v_fmac_f32_e32 v59, v27, v46
	v_mov_b32_dpp v54, v28 row_shr:4 row_mask:0xf bank_mask:0xf bound_ctrl:1
	v_pk_fma_f32 v[8:9], v[10:11], v[46:47], v[8:9] op_sel:[1,0,0]
	v_mov_b32_e32 v55, v28
	v_fmac_f32_e32 v59, v28, v54
	v_mov_b32_dpp v56, v29 row_shr:4 row_mask:0xf bank_mask:0xf bound_ctrl:1
	v_pk_fma_f32 v[8:9], v[12:13], v[54:55], v[8:9] op_sel_hi:[0,1,1]
	v_mov_b32_e32 v57, v29
	v_fmac_f32_e32 v59, v29, v56
	v_mov_b32_dpp v60, v30 row_shr:4 row_mask:0xf bank_mask:0xf bound_ctrl:1
	v_pk_fma_f32 v[8:9], v[12:13], v[56:57], v[8:9] op_sel:[1,0,0]
	v_mov_b32_e32 v61, v30
	v_fmac_f32_e32 v59, v30, v60
	v_pk_fma_f32 v[8:9], v[14:15], v[60:61], v[8:9] op_sel_hi:[0,1,1]
	v_mov_b32_dpp v30, v31 row_shr:4 row_mask:0xf bank_mask:0xf bound_ctrl:1
	v_mov_b32_dpp v10, v32 row_shr:4 row_mask:0xf bank_mask:0xf bound_ctrl:1
	v_pk_fma_f32 v[8:9], v[14:15], v[30:31], v[8:9] op_sel:[1,0,0]
	v_mov_b32_e32 v11, v32
	v_fmac_f32_e32 v59, v31, v30
	v_mov_b32_dpp v24, v33 row_shr:4 row_mask:0xf bank_mask:0xf bound_ctrl:1
	v_pk_fma_f32 v[8:9], v[16:17], v[10:11], v[8:9] op_sel_hi:[0,1,1]
	v_mov_b32_e32 v25, v33
	v_fmac_f32_e32 v59, v32, v10
; DI float softplus_f(float x) { return x > 20.f ? x : log1pf(__expf(x)); }
; DI void gdn_chain(const P& p, int cid, char* smem) {
;     ...
;           const float kp = __builtin_bit_cast(float, __builtin_amdgcn_mov_dpp(__builtin_bit_cast(int, ak[i]), 0x114, 0xF, 0xF, true));
;           gsame += aq[i] * ak[i];
;           kk += kp * ak[i];
;           g21 += aq[i] * kp;
;         }
;         gsame = quad_sum(gsame);
;         kk = quad_sum(kk);
;         g21 = quad_sum(g21);
;         if (qd == 0) {
;           const float za = side[(size_t)(base + tau) * 32 + dir * 8 + h];
;           const float zb = side[(size_t)(base + tau) * 32 + 16 + dir * 8 + h];
;           const float av_ = __expf(-Aexp * softplus_f(za + dtb));
	v_mov_b32_dpp v26, v34 row_shr:4 row_mask:0xf bank_mask:0xf bound_ctrl:1
	v_pk_fma_f32 v[8:9], v[16:17], v[24:25], v[8:9] op_sel:[1,0,0]
	v_mov_b32_e32 v27, v34
	v_fmac_f32_e32 v59, v33, v24
	v_mov_b32_dpp v28, v35 row_shr:4 row_mask:0xf bank_mask:0xf bound_ctrl:1
	v_pk_fma_f32 v[8:9], v[18:19], v[26:27], v[8:9] op_sel_hi:[0,1,1]
	v_mov_b32_e32 v29, v35
	v_fmac_f32_e32 v59, v34, v26
	v_mov_b32_dpp v40, v36 row_shr:4 row_mask:0xf bank_mask:0xf bound_ctrl:1
	v_pk_fma_f32 v[8:9], v[18:19], v[28:29], v[8:9] op_sel:[1,0,0]
	v_mov_b32_e32 v41, v36
	v_fmac_f32_e32 v59, v35, v28
	v_mov_b32_dpp v42, v37 row_shr:4 row_mask:0xf bank_mask:0xf bound_ctrl:1
	v_pk_fma_f32 v[8:9], v[20:21], v[40:41], v[8:9] op_sel_hi:[0,1,1]
	v_mov_b32_e32 v43, v37
	v_fmac_f32_e32 v59, v36, v40
	v_mov_b32_dpp v44, v38 row_shr:4 row_mask:0xf bank_mask:0xf bound_ctrl:1
	v_pk_fma_f32 v[8:9], v[20:21], v[42:43], v[8:9] op_sel:[1,0,0]
	v_mov_b32_e32 v45, v38
	v_fmac_f32_e32 v59, v37, v42
	v_mov_b32_dpp v46, v39 row_shr:4 row_mask:0xf bank_mask:0xf bound_ctrl:1
	v_pk_fma_f32 v[8:9], v[22:23], v[44:45], v[8:9] op_sel_hi:[0,1,1]
	v_mov_b32_e32 v47, v39
	v_fmac_f32_e32 v59, v38, v44
	v_pk_fma_f32 v[8:9], v[22:23], v[46:47], v[8:9] op_sel:[1,0,0]
	v_fmac_f32_e32 v59, v39, v46
	s_nop 0
	v_mov_b32_dpp v11, v9 quad_perm:[1,0,3,2] row_mask:0xf bank_mask:0xf bound_ctrl:1
	v_mov_b32_dpp v10, v8 quad_perm:[1,0,3,2] row_mask:0xf bank_mask:0xf bound_ctrl:1
	v_add_f32_dpp v12, v59, v59 quad_perm:[1,0,3,2] row_mask:0xf bank_mask:0xf bound_ctrl:1
	v_pk_add_f32 v[8:9], v[8:9], v[10:11]
	s_nop 0
	v_mov_b32_dpp v13, v12 quad_perm:[2,3,0,1] row_mask:0xf bank_mask:0xf bound_ctrl:1
	v_mov_b32_dpp v11, v9 quad_perm:[2,3,0,1] row_mask:0xf bank_mask:0xf bound_ctrl:1
	v_mov_b32_dpp v10, v8 quad_perm:[2,3,0,1] row_mask:0xf bank_mask:0xf bound_ctrl:1
	s_and_saveexec_b64 s[0:1], s[76:77]
	s_cbranch_execz .LBB0_965
	v_ashrrev_i32_e32 v59, 31, v58
	v_lshlrev_b64 v[14:15], 7, v[58:59]
	v_lshl_add_u64 v[14:15], s[40:41], 0, v[14:15]
	global_load_dword v16, v[14:15], off
	s_nop 0
	global_load_dword v14, v[14:15], off offset:64
	s_mov_b32 s4, 0x41a00000
	s_waitcnt vmcnt(1)
	v_add_f32_e32 v15, v49, v16
	v_cmp_nlt_f32_e32 vcc, s4, v15
	s_and_saveexec_b64 s[4:5], vcc
	s_cbranch_execz .LBB0_961
	v_mul_f32_e32 v15, 0x3fb8aa3b, v15
	v_exp_f32_e32 v15, v15
	s_mov_b32 s15, 0x3f2aaaab
	v_add_f32_e32 v18, 1.0, v15
	v_frexp_mant_f32_e32 v20, v18
	v_cvt_f64_f32_e32 v[16:17], v18
	v_frexp_exp_i32_f64_e32 v16, v[16:17]
	v_cmp_gt_f32_e32 vcc, s15, v20
	v_add_f32_e32 v19, -1.0, v18
	v_sub_f32_e32 v21, v19, v18
	v_subbrev_co_u32_e32 v24, vcc, 0, v16, vcc
	v_sub_u32_e32 v16, 0, v24
	v_sub_f32_e32 v19, v15, v19
	v_add_f32_e32 v21, 1.0, v21
	v_ldexp_f32 v17, v18, v16
	v_add_f32_e32 v19, v19, v21
	v_add_f32_e32 v18, -1.0, v17
	v_add_f32_e32 v20, 1.0, v17
	v_ldexp_f32 v16, v19, v16
	v_add_f32_e32 v19, 1.0, v18
	v_add_f32_e32 v21, -1.0, v20
	v_sub_f32_e32 v19, v17, v19
	v_sub_f32_e32 v17, v17, v21
	v_add_f32_e32 v19, v16, v19
	v_add_f32_e32 v16, v16, v17
	v_add_f32_e32 v25, v20, v16
	v_rcp_f32_e32 v27, v25
	v_sub_f32_e32 v17, v25, v20
	v_sub_f32_e32 v26, v16, v17
	v_add_f32_e32 v17, v18, v19
	v_mul_f32_e32 v29, v17, v27
	v_sub_f32_e32 v16, v17, v18
	v_mul_f32_e32 v18, v25, v29
	v_fma_f32 v20, v29, v25, -v18
	v_fmac_f32_e32 v20, v29, v26
	v_sub_f32_e32 v28, v19, v16
	v_add_f32_e32 v16, v18, v20
	v_sub_f32_e32 v19, v17, v16
	v_pk_add_f32 v[22:23], v[16:17], v[18:19] neg_lo:[0,1] neg_hi:[0,1]
	v_mov_b32_e32 v21, v16
	v_pk_add_f32 v[16:17], v[22:23], v[20:21] neg_lo:[0,1] neg_hi:[0,1]
	s_mov_b32 s15, 0x3f317218
	v_add_f32_e32 v17, v28, v17
	v_add_f32_e32 v16, v16, v17
	v_add_f32_e32 v17, v19, v16
	v_mul_f32_e32 v28, v27, v17
	v_mul_f32_e32 v18, v25, v28
	v_fma_f32 v20, v28, v25, -v18
	v_fmac_f32_e32 v20, v28, v26
	v_sub_f32_e32 v19, v19, v17
	v_add_f32_e32 v25, v16, v19
	v_add_f32_e32 v16, v18, v20
	v_sub_f32_e32 v19, v17, v16
	v_pk_add_f32 v[22:23], v[16:17], v[18:19] neg_lo:[0,1] neg_hi:[0,1]
	v_mov_b32_e32 v21, v16
	v_pk_add_f32 v[16:17], v[22:23], v[20:21] neg_lo:[0,1] neg_hi:[0,1]
	v_cmp_neq_f32_e32 vcc, s35, v15
	v_add_f32_e32 v17, v25, v17
	v_add_f32_e32 v16, v16, v17
	v_add_f32_e32 v17, v29, v28
	v_add_f32_e32 v16, v19, v16
	v_sub_f32_e32 v18, v17, v29
	v_mul_f32_e32 v16, v27, v16
	v_sub_f32_e32 v18, v28, v18
	v_add_f32_e32 v18, v18, v16
	v_add_f32_e32 v20, v17, v18
	v_mul_f32_e32 v21, v20, v20
	v_fmamk_f32 v16, v21, 0x3e9b6dac, v134
	v_fmaak_f32 v115, v21, v16, 0x3f2aaada
	v_cvt_f32_i32_e32 v16, v24
	v_sub_f32_e32 v17, v20, v17
	v_sub_f32_e32 v17, v18, v17
	v_ldexp_f32 v22, v17, 1
	v_mul_f32_e32 v17, v20, v21
	v_ldexp_f32 v19, v20, 1
	v_pk_mul_f32 v[20:21], v[16:17], v[114:115]
	s_nop 0
	v_fma_f32 v18, v16, s15, -v20
	v_fmac_f32_e32 v18, 0xb102e308, v16
	v_pk_add_f32 v[16:17], v[20:21], v[18:19]
	s_mov_b32 s15, 0x33800000
	v_sub_f32_e32 v19, v17, v19
	v_sub_f32_e32 v19, v21, v19
	v_add_f32_e32 v23, v22, v19
	v_mov_b32_e32 v22, v20
	v_pk_add_f32 v[20:21], v[16:17], v[20:21] neg_lo:[0,1] neg_hi:[0,1]
	v_pk_add_f32 v[24:25], v[16:17], v[22:23]
	v_mov_b32_e32 v19, v16
	v_mov_b32_e32 v21, v25
	v_pk_add_f32 v[26:27], v[18:19], v[20:21] neg_lo:[0,1] neg_hi:[0,1]
	v_pk_add_f32 v[18:19], v[18:19], v[20:21]
	v_mov_b32_e32 v22, v23
	v_pk_add_f32 v[20:21], v[18:19], v[16:17] op_sel:[1,0] op_sel_hi:[0,1] neg_lo:[0,1] neg_hi:[0,1]
	v_pk_add_f32 v[28:29], v[24:25], v[20:21] op_sel_hi:[1,0] neg_lo:[0,1] neg_hi:[0,1]
	v_mov_b32_e32 v24, v25
	v_mov_b32_e32 v25, v19
	v_pk_mov_b32 v[20:21], v[16:17], v[20:21] op_sel:[1,0]
	v_mov_b32_e32 v23, v16
	v_pk_add_f32 v[20:21], v[24:25], v[20:21] neg_lo:[0,1] neg_hi:[0,1]
	v_mov_b32_e32 v28, v26
	v_pk_add_f32 v[16:17], v[22:23], v[20:21] neg_lo:[0,1] neg_hi:[0,1]
	v_mov_b32_e32 v27, v19
	v_pk_add_f32 v[20:21], v[28:29], v[16:17]
	s_nop 0
	v_pk_add_f32 v[22:23], v[20:21], v[20:21] op_sel:[0,1] op_sel_hi:[1,0]
	s_nop 0
	v_pk_add_f32 v[18:19], v[18:19], v[22:23] op_sel:[1,0] op_sel_hi:[0,1]
	v_mov_b32_e32 v21, v18
	v_pk_add_f32 v[24:25], v[20:21], v[26:27] neg_lo:[0,1] neg_hi:[0,1]
	v_mov_b32_e32 v17, v22
	v_sub_f32_e32 v19, v20, v24
	v_pk_add_f32 v[16:17], v[16:17], v[24:25] neg_lo:[0,1] neg_hi:[0,1]
	v_sub_f32_e32 v19, v26, v19
	v_add_f32_e32 v16, v16, v19
	v_add_f32_e32 v16, v16, v17
	v_add_f32_e32 v16, v18, v16
	v_cndmask_b32_e32 v16, v150, v16, vcc
	v_cmp_ngt_f32_e32 vcc, -1.0, v15
	s_nop 1
	v_cndmask_b32_e32 v16, v151, v16, vcc
	v_cmp_neq_f32_e32 vcc, -1.0, v15
	s_nop 1
	v_cndmask_b32_e32 v16, v149, v16, vcc
	v_cmp_lt_f32_e64 vcc, |v15|, s15
	s_nop 1
	v_cndmask_b32_e32 v15, v16, v15, vcc
